# P7 gate-part epilogue: n=0/n=1 store pairs merged into one 16-byte store via v_permlane16_swap; rope-part table loads software-pipelined by one group
# speedup vs baseline: 1.1007x; 1.0018x over previous
.LBB0_1008:
	ds_read_b128 v[152:155], v165
	ds_read_b128 v[156:159], v165 offset:1024
	ds_read_b128 v[170:173], v165 offset:2048
	ds_read_b128 v[174:177], v165 offset:3072
	s_add_u32 s8, s0, 0xfffc0080
	s_addc_u32 s9, s1, -1
	s_cmp_eq_u32 s21, 12
	s_cselect_b32 s11, s29, s9
	s_cselect_b32 s10, s28, s8
	s_cselect_b32 s9, s37, s19
	s_cselect_b32 s8, s36, s14
	v_lshl_add_u64 v[160:161], s[0:1], 0, v[142:143]
	s_add_i32 m0, s26, 0xc000
	ds_read_b128 v[178:181], v166
	ds_read_b128 v[182:185], v166 offset:1024
	ds_read_b128 v[186:189], v166 offset:2048
	ds_read_b128 v[190:193], v166 offset:3072
	ds_read_b128 v[194:197], v166 offset:4096
	ds_read_b128 v[200:203], v166 offset:5120
	ds_read_b128 v[204:207], v166 offset:6144
	ds_read_b128 v[208:211], v166 offset:7168
	global_load_lds_dwordx4 v[160:161], off
	v_lshl_add_u64 v[160:161], s[0:1], 0, v[144:145]
	s_add_i32 m0, s26, 0xe000
	s_nop 0
	global_load_lds_dwordx4 v[160:161], off
	s_waitcnt lgkmcnt(8)
	s_barrier
	s_waitcnt lgkmcnt(0)
	s_setprio 1
	s_waitcnt lgkmcnt(0)
	v_mfma_f32_16x16x32_bf16 v[124:127], v[152:155], v[178:181], v[124:127]
	v_mfma_f32_16x16x32_bf16 v[116:119], v[170:173], v[178:181], v[116:119]
	v_mfma_f32_16x16x32_bf16 v[108:111], v[152:155], v[186:189], v[108:111]
	v_mfma_f32_16x16x32_bf16 v[100:103], v[170:173], v[186:189], v[100:103]
	v_mfma_f32_16x16x32_bf16 v[92:95], v[152:155], v[194:197], v[92:95]
	v_mfma_f32_16x16x32_bf16 v[84:87], v[170:173], v[194:197], v[84:87]
	v_mfma_f32_16x16x32_bf16 v[76:79], v[152:155], v[204:207], v[76:79]
	v_mfma_f32_16x16x32_bf16 v[68:71], v[170:173], v[204:207], v[68:71]
	v_mfma_f32_16x16x32_bf16 v[124:127], v[156:159], v[182:185], v[124:127]
	v_mfma_f32_16x16x32_bf16 v[116:119], v[174:177], v[182:185], v[116:119]
	v_mfma_f32_16x16x32_bf16 v[108:111], v[156:159], v[190:193], v[108:111]
	v_mfma_f32_16x16x32_bf16 v[100:103], v[174:177], v[190:193], v[100:103]
	v_mfma_f32_16x16x32_bf16 v[92:95], v[156:159], v[200:203], v[92:95]
	v_mfma_f32_16x16x32_bf16 v[84:87], v[174:177], v[200:203], v[84:87]
	v_mfma_f32_16x16x32_bf16 v[76:79], v[156:159], v[208:211], v[76:79]
	v_mfma_f32_16x16x32_bf16 v[68:71], v[174:177], v[208:211], v[68:71]
	s_setprio 0
	s_barrier
	s_add_i32 s23, s53, s25
	v_lshl_add_u64 v[160:161], s[8:9], 0, v[128:129]
	s_mov_b32 m0, s23
	ds_read_b128 v[212:215], v167
	ds_read_b128 v[216:219], v167 offset:1024
	ds_read_b128 v[220:223], v167 offset:2048
	ds_read_b128 v[224:227], v167 offset:3072
	global_load_lds_dwordx4 v[160:161], off
	v_lshl_add_u64 v[228:229], s[8:9], 0, v[130:131]
	s_add_i32 m0, s23, 0x2000
	s_nop 0
	global_load_lds_dwordx4 v[228:229], off
	s_barrier
	s_waitcnt lgkmcnt(0)
	s_setprio 1
	s_waitcnt lgkmcnt(0)
	v_mfma_f32_16x16x32_bf16 v[120:123], v[212:215], v[178:181], v[120:123]
	v_mfma_f32_16x16x32_bf16 v[112:115], v[220:223], v[178:181], v[112:115]
	v_mfma_f32_16x16x32_bf16 v[104:107], v[212:215], v[186:189], v[104:107]
	v_mfma_f32_16x16x32_bf16 v[96:99], v[220:223], v[186:189], v[96:99]
	v_mfma_f32_16x16x32_bf16 v[88:91], v[212:215], v[194:197], v[88:91]
	v_mfma_f32_16x16x32_bf16 v[80:83], v[220:223], v[194:197], v[80:83]
	v_mfma_f32_16x16x32_bf16 v[72:75], v[212:215], v[204:207], v[72:75]
	v_mfma_f32_16x16x32_bf16 v[64:67], v[220:223], v[204:207], v[64:67]
	v_mfma_f32_16x16x32_bf16 v[120:123], v[216:219], v[182:185], v[120:123]
	v_mfma_f32_16x16x32_bf16 v[112:115], v[224:227], v[182:185], v[112:115]
	v_mfma_f32_16x16x32_bf16 v[104:107], v[216:219], v[190:193], v[104:107]
	v_mfma_f32_16x16x32_bf16 v[96:99], v[224:227], v[190:193], v[96:99]
	v_mfma_f32_16x16x32_bf16 v[88:91], v[216:219], v[200:203], v[88:91]
	v_mfma_f32_16x16x32_bf16 v[80:83], v[224:227], v[200:203], v[80:83]
	v_mfma_f32_16x16x32_bf16 v[72:75], v[216:219], v[208:211], v[72:75]
	v_mfma_f32_16x16x32_bf16 v[64:67], v[224:227], v[208:211], v[64:67]
	s_setprio 0
	s_mov_b32 m0, s26
	v_lshl_add_u64 v[230:231], s[10:11], 0, v[128:129]
	s_barrier
	ds_read_b128 v[178:181], v166 offset:16384
	ds_read_b128 v[182:185], v166 offset:17408
	ds_read_b128 v[186:189], v166 offset:18432
	ds_read_b128 v[190:193], v166 offset:19456
	ds_read_b128 v[194:197], v166 offset:20480
	ds_read_b128 v[200:203], v166 offset:21504
	ds_read_b128 v[204:207], v166 offset:22528
	ds_read_b128 v[208:211], v166 offset:23552
	global_load_lds_dwordx4 v[230:231], off
	v_lshl_add_u64 v[232:233], s[10:11], 0, v[130:131]
	s_mov_b32 m0, s27
	s_nop 0
	global_load_lds_dwordx4 v[232:233], off
	s_barrier
	s_waitcnt lgkmcnt(0)
	s_setprio 1
	s_waitcnt lgkmcnt(0)
	v_mfma_f32_16x16x32_bf16 v[60:63], v[152:155], v[178:181], v[60:63]
	v_mfma_f32_16x16x32_bf16 v[52:55], v[170:173], v[178:181], v[52:55]
	v_mfma_f32_16x16x32_bf16 v[44:47], v[152:155], v[186:189], v[44:47]
	v_mfma_f32_16x16x32_bf16 v[36:39], v[170:173], v[186:189], v[36:39]
	v_mfma_f32_16x16x32_bf16 v[28:31], v[152:155], v[194:197], v[28:31]
	v_mfma_f32_16x16x32_bf16 v[20:23], v[170:173], v[194:197], v[20:23]
	v_mfma_f32_16x16x32_bf16 v[12:15], v[152:155], v[204:207], v[12:15]
	v_mfma_f32_16x16x32_bf16 v[4:7], v[170:173], v[204:207], v[4:7]
	v_mfma_f32_16x16x32_bf16 v[60:63], v[156:159], v[182:185], v[60:63]
	v_mfma_f32_16x16x32_bf16 v[52:55], v[174:177], v[182:185], v[52:55]
	v_mfma_f32_16x16x32_bf16 v[44:47], v[156:159], v[190:193], v[44:47]
	v_mfma_f32_16x16x32_bf16 v[36:39], v[174:177], v[190:193], v[36:39]
	v_mfma_f32_16x16x32_bf16 v[28:31], v[156:159], v[200:203], v[28:31]
	v_mfma_f32_16x16x32_bf16 v[20:23], v[174:177], v[200:203], v[20:23]
	v_mfma_f32_16x16x32_bf16 v[12:15], v[156:159], v[208:211], v[12:15]
	v_mfma_f32_16x16x32_bf16 v[4:7], v[174:177], v[208:211], v[4:7]
	s_setprio 0
	s_barrier
	s_add_u32 s42, s8, 0x40000
	s_addc_u32 s43, s9, 0
	s_add_i32 s23, s56, s25
	v_lshl_add_u64 v[152:153], s[42:43], 0, v[128:129]
	s_mov_b32 m0, s23
	s_nop 0
	global_load_lds_dwordx4 v[152:153], off
	v_lshl_add_u64 v[152:153], s[42:43], 0, v[130:131]
	s_add_i32 m0, s23, 0x2000
	s_nop 0
	global_load_lds_dwordx4 v[152:153], off
	s_waitcnt vmcnt(6)
	s_barrier
	s_setprio 1
	v_mfma_f32_16x16x32_bf16 v[56:59], v[212:215], v[178:181], v[56:59]
	v_mfma_f32_16x16x32_bf16 v[48:51], v[220:223], v[178:181], v[48:51]
	v_mfma_f32_16x16x32_bf16 v[40:43], v[212:215], v[186:189], v[40:43]
	v_mfma_f32_16x16x32_bf16 v[32:35], v[220:223], v[186:189], v[32:35]
	v_mfma_f32_16x16x32_bf16 v[24:27], v[212:215], v[194:197], v[24:27]
	v_mfma_f32_16x16x32_bf16 v[16:19], v[220:223], v[194:197], v[16:19]
	v_mfma_f32_16x16x32_bf16 v[8:11], v[212:215], v[204:207], v[8:11]
	v_mfma_f32_16x16x32_bf16 v[0:3], v[220:223], v[204:207], v[0:3]
	v_mfma_f32_16x16x32_bf16 v[56:59], v[216:219], v[182:185], v[56:59]
	v_mfma_f32_16x16x32_bf16 v[48:51], v[224:227], v[182:185], v[48:51]
	v_mfma_f32_16x16x32_bf16 v[40:43], v[216:219], v[190:193], v[40:43]
	v_mfma_f32_16x16x32_bf16 v[32:35], v[224:227], v[190:193], v[32:35]
	v_mfma_f32_16x16x32_bf16 v[24:27], v[216:219], v[200:203], v[24:27]
	v_mfma_f32_16x16x32_bf16 v[16:19], v[224:227], v[200:203], v[16:19]
	v_mfma_f32_16x16x32_bf16 v[8:11], v[216:219], v[208:211], v[8:11]
	v_mfma_f32_16x16x32_bf16 v[0:3], v[224:227], v[208:211], v[0:3]
	s_setprio 0
	s_add_i32 s23, 0, 0x18000
	v_add_u32_e32 v132, s23, v163
	s_barrier
	ds_read_b128 v[152:155], v132
	ds_read_b128 v[156:159], v132 offset:1024
	ds_read_b128 v[170:173], v132 offset:2048
	ds_read_b128 v[174:177], v132 offset:3072
	s_add_u32 s10, s10, 0x40000
	s_addc_u32 s11, s11, 0
	s_mov_b32 m0, s39
	v_lshl_add_u64 v[212:213], s[10:11], 0, v[128:129]
	ds_read_b128 v[178:181], v166 offset:32768
	ds_read_b128 v[182:185], v166 offset:33792
	ds_read_b128 v[186:189], v166 offset:34816
	ds_read_b128 v[190:193], v166 offset:35840
	ds_read_b128 v[194:197], v166 offset:36864
	ds_read_b128 v[200:203], v166 offset:37888
	ds_read_b128 v[204:207], v166 offset:38912
	ds_read_b128 v[208:211], v166 offset:39936
	global_load_lds_dwordx4 v[212:213], off
	v_lshl_add_u64 v[212:213], s[10:11], 0, v[130:131]
	s_mov_b32 m0, s41
	s_nop 0
	global_load_lds_dwordx4 v[212:213], off
	s_waitcnt lgkmcnt(8)
	s_barrier
	s_waitcnt lgkmcnt(0)
	s_setprio 1
	s_waitcnt lgkmcnt(0)
	v_mfma_f32_16x16x32_bf16 v[124:127], v[152:155], v[178:181], v[124:127]
	v_mfma_f32_16x16x32_bf16 v[116:119], v[170:173], v[178:181], v[116:119]
	v_mfma_f32_16x16x32_bf16 v[108:111], v[152:155], v[186:189], v[108:111]
	v_mfma_f32_16x16x32_bf16 v[100:103], v[170:173], v[186:189], v[100:103]
	v_mfma_f32_16x16x32_bf16 v[92:95], v[152:155], v[194:197], v[92:95]
	v_mfma_f32_16x16x32_bf16 v[84:87], v[170:173], v[194:197], v[84:87]
	v_mfma_f32_16x16x32_bf16 v[76:79], v[152:155], v[204:207], v[76:79]
	v_mfma_f32_16x16x32_bf16 v[68:71], v[170:173], v[204:207], v[68:71]
	v_mfma_f32_16x16x32_bf16 v[124:127], v[156:159], v[182:185], v[124:127]
	v_mfma_f32_16x16x32_bf16 v[116:119], v[174:177], v[182:185], v[116:119]
	v_mfma_f32_16x16x32_bf16 v[108:111], v[156:159], v[190:193], v[108:111]
	v_mfma_f32_16x16x32_bf16 v[100:103], v[174:177], v[190:193], v[100:103]
	v_mfma_f32_16x16x32_bf16 v[92:95], v[156:159], v[200:203], v[92:95]
	v_mfma_f32_16x16x32_bf16 v[84:87], v[174:177], v[200:203], v[84:87]
	v_mfma_f32_16x16x32_bf16 v[76:79], v[156:159], v[208:211], v[76:79]
	v_mfma_f32_16x16x32_bf16 v[68:71], v[174:177], v[208:211], v[68:71]
	s_setprio 0
	s_barrier
	s_add_i32 s10, 0, 0x1c000
	s_add_i32 s11, s23, s25
	v_add_u32_e32 v132, s10, v163
	v_lshl_add_u64 v[160:161], v[160:161], 0, s[16:17]
	s_mov_b32 m0, s11
	ds_read_b128 v[212:215], v132
	ds_read_b128 v[216:219], v132 offset:1024
	ds_read_b128 v[220:223], v132 offset:2048
	ds_read_b128 v[224:227], v132 offset:3072
	global_load_lds_dwordx4 v[160:161], off
	v_lshl_add_u64 v[160:161], v[228:229], 0, s[16:17]
	s_add_i32 m0, s11, 0x2000
	s_nop 0
	global_load_lds_dwordx4 v[160:161], off
	s_barrier
	s_waitcnt lgkmcnt(0)
	s_setprio 1
	s_waitcnt lgkmcnt(0)
	v_mfma_f32_16x16x32_bf16 v[120:123], v[212:215], v[178:181], v[120:123]
	v_mfma_f32_16x16x32_bf16 v[112:115], v[220:223], v[178:181], v[112:115]
	v_mfma_f32_16x16x32_bf16 v[104:107], v[212:215], v[186:189], v[104:107]
	v_mfma_f32_16x16x32_bf16 v[96:99], v[220:223], v[186:189], v[96:99]
	v_mfma_f32_16x16x32_bf16 v[88:91], v[212:215], v[194:197], v[88:91]
	v_mfma_f32_16x16x32_bf16 v[80:83], v[220:223], v[194:197], v[80:83]
	v_mfma_f32_16x16x32_bf16 v[72:75], v[212:215], v[204:207], v[72:75]
	v_mfma_f32_16x16x32_bf16 v[64:67], v[220:223], v[204:207], v[64:67]
	v_mfma_f32_16x16x32_bf16 v[120:123], v[216:219], v[182:185], v[120:123]
	v_mfma_f32_16x16x32_bf16 v[112:115], v[224:227], v[182:185], v[112:115]
	v_mfma_f32_16x16x32_bf16 v[104:107], v[216:219], v[190:193], v[104:107]
	v_mfma_f32_16x16x32_bf16 v[96:99], v[224:227], v[190:193], v[96:99]
	v_mfma_f32_16x16x32_bf16 v[88:91], v[216:219], v[200:203], v[88:91]
	v_mfma_f32_16x16x32_bf16 v[80:83], v[224:227], v[200:203], v[80:83]
	v_mfma_f32_16x16x32_bf16 v[72:75], v[216:219], v[208:211], v[72:75]
	v_mfma_f32_16x16x32_bf16 v[64:67], v[224:227], v[208:211], v[64:67]
	s_setprio 0
	s_mov_b32 m0, s50
	v_lshl_add_u64 v[160:161], v[230:231], 0, s[16:17]
	s_barrier
	ds_read_b128 v[178:181], v166 offset:49152
	ds_read_b128 v[182:185], v166 offset:50176
	ds_read_b128 v[186:189], v166 offset:51200
	ds_read_b128 v[190:193], v166 offset:52224
	ds_read_b128 v[194:197], v166 offset:53248
	ds_read_b128 v[200:203], v166 offset:54272
	ds_read_b128 v[204:207], v166 offset:55296
	ds_read_b128 v[208:211], v166 offset:56320
	global_load_lds_dwordx4 v[160:161], off
	v_lshl_add_u64 v[160:161], v[232:233], 0, s[16:17]
	s_mov_b32 m0, s51
	s_nop 0
	global_load_lds_dwordx4 v[160:161], off
	s_barrier
	s_waitcnt lgkmcnt(0)
	s_setprio 1
	s_waitcnt lgkmcnt(0)
	v_mfma_f32_16x16x32_bf16 v[60:63], v[152:155], v[178:181], v[60:63]
	v_mfma_f32_16x16x32_bf16 v[52:55], v[170:173], v[178:181], v[52:55]
	v_mfma_f32_16x16x32_bf16 v[44:47], v[152:155], v[186:189], v[44:47]
	v_mfma_f32_16x16x32_bf16 v[36:39], v[170:173], v[186:189], v[36:39]
	v_mfma_f32_16x16x32_bf16 v[28:31], v[152:155], v[194:197], v[28:31]
	v_mfma_f32_16x16x32_bf16 v[20:23], v[170:173], v[194:197], v[20:23]
	v_mfma_f32_16x16x32_bf16 v[12:15], v[152:155], v[204:207], v[12:15]
	v_mfma_f32_16x16x32_bf16 v[4:7], v[170:173], v[204:207], v[4:7]
	v_mfma_f32_16x16x32_bf16 v[60:63], v[156:159], v[182:185], v[60:63]
	v_mfma_f32_16x16x32_bf16 v[52:55], v[174:177], v[182:185], v[52:55]
	v_mfma_f32_16x16x32_bf16 v[44:47], v[156:159], v[190:193], v[44:47]
	v_mfma_f32_16x16x32_bf16 v[36:39], v[174:177], v[190:193], v[36:39]
	v_mfma_f32_16x16x32_bf16 v[28:31], v[156:159], v[200:203], v[28:31]
	v_mfma_f32_16x16x32_bf16 v[20:23], v[174:177], v[200:203], v[20:23]
	v_mfma_f32_16x16x32_bf16 v[12:15], v[156:159], v[208:211], v[12:15]
	v_mfma_f32_16x16x32_bf16 v[4:7], v[174:177], v[208:211], v[4:7]
	s_setprio 0
	s_barrier
	s_add_u32 s8, s8, 0x40080
	s_addc_u32 s9, s9, 0
	s_add_i32 s10, s10, s25
	v_lshl_add_u64 v[152:153], s[8:9], 0, v[128:129]
	s_mov_b32 m0, s10
	s_nop 0
	global_load_lds_dwordx4 v[152:153], off
	v_lshl_add_u64 v[152:153], s[8:9], 0, v[130:131]
	s_add_i32 m0, s10, 0x2000
	s_nop 0
	global_load_lds_dwordx4 v[152:153], off
	s_waitcnt vmcnt(6)
	s_barrier
	s_setprio 1
	v_mfma_f32_16x16x32_bf16 v[56:59], v[212:215], v[178:181], v[56:59]
	v_mfma_f32_16x16x32_bf16 v[48:51], v[220:223], v[178:181], v[48:51]
	v_mfma_f32_16x16x32_bf16 v[40:43], v[212:215], v[186:189], v[40:43]
	v_mfma_f32_16x16x32_bf16 v[32:35], v[220:223], v[186:189], v[32:35]
	v_mfma_f32_16x16x32_bf16 v[24:27], v[212:215], v[194:197], v[24:27]
	v_mfma_f32_16x16x32_bf16 v[16:19], v[220:223], v[194:197], v[16:19]
	v_mfma_f32_16x16x32_bf16 v[8:11], v[212:215], v[204:207], v[8:11]
	v_mfma_f32_16x16x32_bf16 v[0:3], v[220:223], v[204:207], v[0:3]
	v_mfma_f32_16x16x32_bf16 v[56:59], v[216:219], v[182:185], v[56:59]
	v_mfma_f32_16x16x32_bf16 v[48:51], v[224:227], v[182:185], v[48:51]
	v_mfma_f32_16x16x32_bf16 v[40:43], v[216:219], v[190:193], v[40:43]
	v_mfma_f32_16x16x32_bf16 v[32:35], v[224:227], v[190:193], v[32:35]
	v_mfma_f32_16x16x32_bf16 v[24:27], v[216:219], v[200:203], v[24:27]
	v_mfma_f32_16x16x32_bf16 v[16:19], v[224:227], v[200:203], v[16:19]
	v_mfma_f32_16x16x32_bf16 v[8:11], v[216:219], v[208:211], v[8:11]
	v_mfma_f32_16x16x32_bf16 v[0:3], v[224:227], v[208:211], v[0:3]
	s_setprio 0
	s_add_i32 s21, s21, 2
	s_add_u32 s0, s0, 0x100
	s_addc_u32 s1, s1, 0
	s_add_u32 s14, s14, 0x100
	s_addc_u32 s19, s19, 0
	s_cmp_gt_u32 s21, 13
	s_barrier
	s_cbranch_scc0 .LBB0_1008
	s_cmp_gt_i32 s38, 7
	s_mov_b64 s[0:1], -1
	s_cbranch_scc0 .LBB0_1143
	s_cmp_lt_u32 s38, 16
	s_cbranch_scc1 .LBB0_1012
	v_and_b32_e32 v210, 16, v198
	v_lshrrev_b32_e32 v209, 1, v210
	v_add_u32_e32 v210, v210, v209
	v_add_u32_e32 v208, v150, v210
	v_mov_b32_e32 v209, 0
	v_lshl_add_u32 v152, s40, 8, v162
	v_mul_f32_e32 v151, 0xbfb8aa3b, v125
	v_ashrrev_i32_e32 v153, 31, v152
	v_mul_f32_e32 v132, 0xbfb8aa3b, v124
	v_exp_f32_e32 v151, v151
	v_mul_f32_e32 v156, 0xbfb8aa3b, v127
	v_exp_f32_e32 v132, v132
	v_lshlrev_b64 v[154:155], 12, v[152:153]
	v_mul_f32_e32 v153, 0xbfb8aa3b, v126
	v_exp_f32_e32 v156, v156
	v_exp_f32_e32 v153, v153
	v_add_f32_e32 v151, 1.0, v151
	v_add_f32_e32 v132, 1.0, v132
	v_rcp_f32_e32 v151, v151
	v_add_f32_e32 v156, 1.0, v156
	s_lshl_b32 s0, s38, 8
	v_rcp_f32_e32 v132, v132
	v_add_f32_e32 v153, 1.0, v153
	v_rcp_f32_e32 v156, v156
	v_readlane_b32 s8, v254, 38
	s_add_i32 s14, s0, 0xfffff000
	v_rcp_f32_e32 v153, v153
	v_readlane_b32 s9, v254, 39
	s_lshl_b64 s[0:1], s[14:15], 1
	v_mul_f32_e32 v151, v125, v151
	v_lshl_add_u64 v[154:155], s[8:9], 0, v[154:155]
	v_lshl_add_u64 v[154:155], v[154:155], 0, s[0:1]
	s_mov_b32 s19, s15
	v_mul_f32_e32 v132, v124, v132
	v_mul_f32_e32 v157, v127, v156
	v_cvt_pk_bf16_f32 v200, v132, v151
	v_lshl_add_u64 v[154:155], v[154:155], 0, s[18:19]
	v_mov_b32_e32 v151, v133
	v_mul_f32_e32 v153, v126, v153
	v_cvt_pk_bf16_f32 v201, v153, v157
	v_lshl_add_u64 v[154:155], v[154:155], 0, v[208:209]
	v_mul_f32_e32 v157, 0xbfb8aa3b, v119
	v_mul_f32_e32 v132, 0xbfb8aa3b, v116
	v_mul_f32_e32 v153, 0xbfb8aa3b, v117
	v_mul_f32_e32 v156, 0xbfb8aa3b, v118
	v_exp_f32_e32 v157, v157
	v_exp_f32_e32 v132, v132
	v_exp_f32_e32 v153, v153
	v_exp_f32_e32 v156, v156
	v_add_f32_e32 v157, 1.0, v157
	v_add_f32_e32 v132, 1.0, v132
	v_add_f32_e32 v153, 1.0, v153
	v_add_f32_e32 v156, 1.0, v156
	v_rcp_f32_e32 v157, v157
	v_rcp_f32_e32 v132, v132
	v_rcp_f32_e32 v153, v153
	v_rcp_f32_e32 v156, v156
	v_mul_f32_e32 v157, v119, v157
	v_mul_f32_e32 v132, v116, v132
	v_mul_f32_e32 v153, v117, v153
	v_mul_f32_e32 v158, v118, v156
	v_cvt_pk_bf16_f32 v202, v132, v153
	v_cvt_pk_bf16_f32 v203, v158, v157
	s_nop 1
	v_permlane16_swap_b32_e32 v200, v202
	v_permlane16_swap_b32_e32 v201, v203
	global_store_dwordx4 v[154:155], v[200:203], off
	v_mul_f32_e32 v157, 0xbfb8aa3b, v123
	v_mul_f32_e32 v132, 0xbfb8aa3b, v120
	v_mul_f32_e32 v153, 0xbfb8aa3b, v121
	v_mul_f32_e32 v156, 0xbfb8aa3b, v122
	v_exp_f32_e32 v157, v157
	v_exp_f32_e32 v132, v132
	v_exp_f32_e32 v153, v153
	v_exp_f32_e32 v156, v156
	v_add_f32_e32 v157, 1.0, v157
	v_add_f32_e32 v132, 1.0, v132
	v_add_f32_e32 v153, 1.0, v153
	v_add_f32_e32 v156, 1.0, v156
	v_rcp_f32_e32 v157, v157
	v_rcp_f32_e32 v132, v132
	v_rcp_f32_e32 v153, v153
	v_rcp_f32_e32 v156, v156
	v_mul_f32_e32 v157, v123, v157
	v_mul_f32_e32 v132, v120, v132
	v_mul_f32_e32 v153, v121, v153
	v_mul_f32_e32 v158, v122, v156
	v_cvt_pk_bf16_f32 v204, v132, v153
	v_cvt_pk_bf16_f32 v205, v158, v157
	v_mul_f32_e32 v157, 0xbfb8aa3b, v115
	v_mul_f32_e32 v132, 0xbfb8aa3b, v112
	v_mul_f32_e32 v153, 0xbfb8aa3b, v113
	v_mul_f32_e32 v156, 0xbfb8aa3b, v114
	v_exp_f32_e32 v157, v157
	v_exp_f32_e32 v132, v132
	v_exp_f32_e32 v153, v153
	v_exp_f32_e32 v156, v156
	v_add_f32_e32 v157, 1.0, v157
	v_add_f32_e32 v132, 1.0, v132
	v_add_f32_e32 v153, 1.0, v153
	v_add_f32_e32 v156, 1.0, v156
	v_rcp_f32_e32 v157, v157
	v_rcp_f32_e32 v132, v132
	v_rcp_f32_e32 v153, v153
	v_rcp_f32_e32 v156, v156
	v_mul_f32_e32 v157, v115, v157
	v_mul_f32_e32 v132, v112, v132
	v_mul_f32_e32 v153, v113, v153
	v_mul_f32_e32 v158, v114, v156
	v_cvt_pk_bf16_f32 v206, v132, v153
	v_cvt_pk_bf16_f32 v207, v158, v157
	s_nop 1
	v_permlane16_swap_b32_e32 v204, v206
	v_permlane16_swap_b32_e32 v205, v207
	global_store_dwordx4 v[154:155], v[204:207], off offset:256
	v_mul_f32_e32 v157, 0xbfb8aa3b, v111
	v_mul_f32_e32 v132, 0xbfb8aa3b, v108
	v_mul_f32_e32 v153, 0xbfb8aa3b, v109
	v_mul_f32_e32 v156, 0xbfb8aa3b, v110
	v_exp_f32_e32 v157, v157
	v_exp_f32_e32 v132, v132
	v_exp_f32_e32 v153, v153
	v_exp_f32_e32 v156, v156
	v_or_b32_e32 v154, 16, v152
	v_add_f32_e32 v157, 1.0, v157
	v_ashrrev_i32_e32 v155, 31, v154
	v_add_f32_e32 v132, 1.0, v132
	v_add_f32_e32 v153, 1.0, v153
	v_add_f32_e32 v156, 1.0, v156
	v_rcp_f32_e32 v157, v157
	v_lshlrev_b64 v[154:155], 12, v[154:155]
	v_rcp_f32_e32 v132, v132
	v_rcp_f32_e32 v153, v153
	v_rcp_f32_e32 v156, v156
	v_lshl_add_u64 v[154:155], s[8:9], 0, v[154:155]
	v_lshl_add_u64 v[154:155], v[154:155], 0, s[0:1]
	v_mul_f32_e32 v157, v111, v157
	v_lshl_add_u64 v[154:155], v[154:155], 0, s[18:19]
	v_mul_f32_e32 v132, v108, v132
	v_mul_f32_e32 v153, v109, v153
	v_mul_f32_e32 v158, v110, v156
	v_cvt_pk_bf16_f32 v200, v132, v153
	v_cvt_pk_bf16_f32 v201, v158, v157
	v_lshl_add_u64 v[154:155], v[154:155], 0, v[208:209]
	v_mul_f32_e32 v157, 0xbfb8aa3b, v103
	v_mul_f32_e32 v132, 0xbfb8aa3b, v100
	v_mul_f32_e32 v153, 0xbfb8aa3b, v101
	v_mul_f32_e32 v156, 0xbfb8aa3b, v102
	v_exp_f32_e32 v157, v157
	v_exp_f32_e32 v132, v132
	v_exp_f32_e32 v153, v153
	v_exp_f32_e32 v156, v156
	v_add_f32_e32 v157, 1.0, v157
	v_add_f32_e32 v132, 1.0, v132
	v_add_f32_e32 v153, 1.0, v153
	v_add_f32_e32 v156, 1.0, v156
	v_rcp_f32_e32 v157, v157
	v_rcp_f32_e32 v132, v132
	v_rcp_f32_e32 v153, v153
	v_rcp_f32_e32 v156, v156
	v_mul_f32_e32 v157, v103, v157
	v_mul_f32_e32 v132, v100, v132
	v_mul_f32_e32 v153, v101, v153
	v_mul_f32_e32 v158, v102, v156
	v_cvt_pk_bf16_f32 v202, v132, v153
	v_cvt_pk_bf16_f32 v203, v158, v157
	s_nop 1
	v_permlane16_swap_b32_e32 v200, v202
	v_permlane16_swap_b32_e32 v201, v203
	global_store_dwordx4 v[154:155], v[200:203], off
	v_mul_f32_e32 v157, 0xbfb8aa3b, v107
	v_mul_f32_e32 v132, 0xbfb8aa3b, v104
	v_mul_f32_e32 v153, 0xbfb8aa3b, v105
	v_mul_f32_e32 v156, 0xbfb8aa3b, v106
	v_exp_f32_e32 v157, v157
	v_exp_f32_e32 v132, v132
	v_exp_f32_e32 v153, v153
	v_exp_f32_e32 v156, v156
	v_add_f32_e32 v157, 1.0, v157
	v_add_f32_e32 v132, 1.0, v132
	v_add_f32_e32 v153, 1.0, v153
	v_add_f32_e32 v156, 1.0, v156
	v_rcp_f32_e32 v157, v157
	v_rcp_f32_e32 v132, v132
	v_rcp_f32_e32 v153, v153
	v_rcp_f32_e32 v156, v156
	v_mul_f32_e32 v157, v107, v157
	v_mul_f32_e32 v132, v104, v132
	v_mul_f32_e32 v153, v105, v153
	v_mul_f32_e32 v158, v106, v156
	v_cvt_pk_bf16_f32 v204, v132, v153
	v_cvt_pk_bf16_f32 v205, v158, v157
	v_mul_f32_e32 v157, 0xbfb8aa3b, v99
	v_mul_f32_e32 v132, 0xbfb8aa3b, v96
	v_mul_f32_e32 v153, 0xbfb8aa3b, v97
	v_mul_f32_e32 v156, 0xbfb8aa3b, v98
	v_exp_f32_e32 v157, v157
	v_exp_f32_e32 v132, v132
	v_exp_f32_e32 v153, v153
	v_exp_f32_e32 v156, v156
	v_add_f32_e32 v157, 1.0, v157
	v_add_f32_e32 v132, 1.0, v132
	v_add_f32_e32 v153, 1.0, v153
	v_add_f32_e32 v156, 1.0, v156
	v_rcp_f32_e32 v157, v157
	v_rcp_f32_e32 v132, v132
	v_rcp_f32_e32 v153, v153
	v_rcp_f32_e32 v156, v156
	v_mul_f32_e32 v157, v99, v157
	v_mul_f32_e32 v132, v96, v132
	v_mul_f32_e32 v153, v97, v153
	v_mul_f32_e32 v158, v98, v156
	v_cvt_pk_bf16_f32 v206, v132, v153
	v_cvt_pk_bf16_f32 v207, v158, v157
	s_nop 1
	v_permlane16_swap_b32_e32 v204, v206
	v_permlane16_swap_b32_e32 v205, v207
	global_store_dwordx4 v[154:155], v[204:207], off offset:256
	v_mul_f32_e32 v157, 0xbfb8aa3b, v95
	v_mul_f32_e32 v132, 0xbfb8aa3b, v92
	v_mul_f32_e32 v153, 0xbfb8aa3b, v93
	v_mul_f32_e32 v156, 0xbfb8aa3b, v94
	v_exp_f32_e32 v157, v157
	v_exp_f32_e32 v132, v132
	v_exp_f32_e32 v153, v153
	v_exp_f32_e32 v156, v156
	v_or_b32_e32 v154, 32, v152
	v_add_f32_e32 v157, 1.0, v157
	v_ashrrev_i32_e32 v155, 31, v154
	v_add_f32_e32 v132, 1.0, v132
	v_add_f32_e32 v153, 1.0, v153
	v_add_f32_e32 v156, 1.0, v156
	v_rcp_f32_e32 v157, v157
	v_lshlrev_b64 v[154:155], 12, v[154:155]
	v_rcp_f32_e32 v132, v132
	v_rcp_f32_e32 v153, v153
	v_rcp_f32_e32 v156, v156
	v_lshl_add_u64 v[154:155], s[8:9], 0, v[154:155]
	v_lshl_add_u64 v[154:155], v[154:155], 0, s[0:1]
	v_mul_f32_e32 v157, v95, v157
	v_lshl_add_u64 v[154:155], v[154:155], 0, s[18:19]
	v_mul_f32_e32 v132, v92, v132
	v_mul_f32_e32 v153, v93, v153
	v_mul_f32_e32 v158, v94, v156
	v_cvt_pk_bf16_f32 v200, v132, v153
	v_cvt_pk_bf16_f32 v201, v158, v157
	v_lshl_add_u64 v[154:155], v[154:155], 0, v[208:209]
	v_mul_f32_e32 v157, 0xbfb8aa3b, v87
	v_mul_f32_e32 v132, 0xbfb8aa3b, v84
	v_mul_f32_e32 v153, 0xbfb8aa3b, v85
	v_mul_f32_e32 v156, 0xbfb8aa3b, v86
	v_exp_f32_e32 v157, v157
	v_exp_f32_e32 v132, v132
	v_exp_f32_e32 v153, v153
	v_exp_f32_e32 v156, v156
	v_add_f32_e32 v157, 1.0, v157
	v_add_f32_e32 v132, 1.0, v132
	v_add_f32_e32 v153, 1.0, v153
	v_add_f32_e32 v156, 1.0, v156
	v_rcp_f32_e32 v157, v157
	v_rcp_f32_e32 v132, v132
	v_rcp_f32_e32 v153, v153
	v_rcp_f32_e32 v156, v156
	v_mul_f32_e32 v157, v87, v157
	v_mul_f32_e32 v132, v84, v132
	v_mul_f32_e32 v153, v85, v153
	v_mul_f32_e32 v158, v86, v156
	v_cvt_pk_bf16_f32 v202, v132, v153
	v_cvt_pk_bf16_f32 v203, v158, v157
	s_nop 1
	v_permlane16_swap_b32_e32 v200, v202
	v_permlane16_swap_b32_e32 v201, v203
	global_store_dwordx4 v[154:155], v[200:203], off
	v_mul_f32_e32 v157, 0xbfb8aa3b, v91
	v_mul_f32_e32 v132, 0xbfb8aa3b, v88
	v_mul_f32_e32 v153, 0xbfb8aa3b, v89
	v_mul_f32_e32 v156, 0xbfb8aa3b, v90
	v_exp_f32_e32 v157, v157
	v_exp_f32_e32 v132, v132
	v_exp_f32_e32 v153, v153
	v_exp_f32_e32 v156, v156
	v_add_f32_e32 v157, 1.0, v157
	v_add_f32_e32 v132, 1.0, v132
	v_add_f32_e32 v153, 1.0, v153
	v_add_f32_e32 v156, 1.0, v156
	v_rcp_f32_e32 v157, v157
	v_rcp_f32_e32 v132, v132
	v_rcp_f32_e32 v153, v153
	v_rcp_f32_e32 v156, v156
	v_mul_f32_e32 v157, v91, v157
	v_mul_f32_e32 v132, v88, v132
	v_mul_f32_e32 v153, v89, v153
	v_mul_f32_e32 v158, v90, v156
	v_cvt_pk_bf16_f32 v204, v132, v153
	v_cvt_pk_bf16_f32 v205, v158, v157
	v_mul_f32_e32 v157, 0xbfb8aa3b, v83
	v_mul_f32_e32 v132, 0xbfb8aa3b, v80
	v_mul_f32_e32 v153, 0xbfb8aa3b, v81
	v_mul_f32_e32 v156, 0xbfb8aa3b, v82
	v_exp_f32_e32 v157, v157
	v_exp_f32_e32 v132, v132
	v_exp_f32_e32 v153, v153
	v_exp_f32_e32 v156, v156
	v_add_f32_e32 v157, 1.0, v157
	v_add_f32_e32 v132, 1.0, v132
	v_add_f32_e32 v153, 1.0, v153
	v_add_f32_e32 v156, 1.0, v156
	v_rcp_f32_e32 v157, v157
	v_rcp_f32_e32 v132, v132
	v_rcp_f32_e32 v153, v153
	v_rcp_f32_e32 v156, v156
	v_mul_f32_e32 v157, v83, v157
	v_mul_f32_e32 v132, v80, v132
	v_mul_f32_e32 v153, v81, v153
	v_mul_f32_e32 v158, v82, v156
	v_cvt_pk_bf16_f32 v206, v132, v153
	v_cvt_pk_bf16_f32 v207, v158, v157
	s_nop 1
	v_permlane16_swap_b32_e32 v204, v206
	v_permlane16_swap_b32_e32 v205, v207
	global_store_dwordx4 v[154:155], v[204:207], off offset:256
	v_mul_f32_e32 v157, 0xbfb8aa3b, v79
	v_mul_f32_e32 v132, 0xbfb8aa3b, v76
	v_mul_f32_e32 v153, 0xbfb8aa3b, v77
	v_mul_f32_e32 v156, 0xbfb8aa3b, v78
	v_exp_f32_e32 v157, v157
	v_exp_f32_e32 v132, v132
	v_exp_f32_e32 v153, v153
	v_exp_f32_e32 v156, v156
	v_or_b32_e32 v154, 48, v152
	v_add_f32_e32 v157, 1.0, v157
	v_ashrrev_i32_e32 v155, 31, v154
	v_add_f32_e32 v132, 1.0, v132
	v_add_f32_e32 v153, 1.0, v153
	v_add_f32_e32 v156, 1.0, v156
	v_rcp_f32_e32 v157, v157
	v_lshlrev_b64 v[154:155], 12, v[154:155]
	v_rcp_f32_e32 v132, v132
	v_rcp_f32_e32 v153, v153
	v_rcp_f32_e32 v156, v156
	v_lshl_add_u64 v[154:155], s[8:9], 0, v[154:155]
	v_lshl_add_u64 v[154:155], v[154:155], 0, s[0:1]
	v_mul_f32_e32 v157, v79, v157
	v_lshl_add_u64 v[154:155], v[154:155], 0, s[18:19]
	v_mul_f32_e32 v132, v76, v132
	v_mul_f32_e32 v153, v77, v153
	v_mul_f32_e32 v158, v78, v156
	v_cvt_pk_bf16_f32 v200, v132, v153
	v_cvt_pk_bf16_f32 v201, v158, v157
	v_lshl_add_u64 v[154:155], v[154:155], 0, v[208:209]
	v_mul_f32_e32 v157, 0xbfb8aa3b, v71
	v_mul_f32_e32 v132, 0xbfb8aa3b, v68
	v_mul_f32_e32 v153, 0xbfb8aa3b, v69
	v_mul_f32_e32 v156, 0xbfb8aa3b, v70
	v_exp_f32_e32 v157, v157
	v_exp_f32_e32 v132, v132
	v_exp_f32_e32 v153, v153
	v_exp_f32_e32 v156, v156
	v_add_f32_e32 v157, 1.0, v157
	v_add_f32_e32 v132, 1.0, v132
	v_add_f32_e32 v153, 1.0, v153
	v_add_f32_e32 v156, 1.0, v156
	v_rcp_f32_e32 v157, v157
	v_rcp_f32_e32 v132, v132
	v_rcp_f32_e32 v153, v153
	v_rcp_f32_e32 v156, v156
	v_mul_f32_e32 v157, v71, v157
	v_mul_f32_e32 v132, v68, v132
	v_mul_f32_e32 v153, v69, v153
	v_mul_f32_e32 v158, v70, v156
	v_cvt_pk_bf16_f32 v202, v132, v153
	v_cvt_pk_bf16_f32 v203, v158, v157
	s_nop 1
	v_permlane16_swap_b32_e32 v200, v202
	v_permlane16_swap_b32_e32 v201, v203
	global_store_dwordx4 v[154:155], v[200:203], off
	v_mul_f32_e32 v157, 0xbfb8aa3b, v75
	v_mul_f32_e32 v132, 0xbfb8aa3b, v72
	v_mul_f32_e32 v153, 0xbfb8aa3b, v73
	v_mul_f32_e32 v156, 0xbfb8aa3b, v74
	v_exp_f32_e32 v157, v157
	v_exp_f32_e32 v132, v132
	v_exp_f32_e32 v153, v153
	v_exp_f32_e32 v156, v156
	v_add_f32_e32 v157, 1.0, v157
	v_add_f32_e32 v132, 1.0, v132
	v_add_f32_e32 v153, 1.0, v153
	v_add_f32_e32 v156, 1.0, v156
	v_rcp_f32_e32 v157, v157
	v_rcp_f32_e32 v132, v132
	v_rcp_f32_e32 v153, v153
	v_rcp_f32_e32 v156, v156
	v_mul_f32_e32 v157, v75, v157
	v_mul_f32_e32 v132, v72, v132
	v_mul_f32_e32 v153, v73, v153
	v_mul_f32_e32 v158, v74, v156
	v_cvt_pk_bf16_f32 v204, v132, v153
	v_cvt_pk_bf16_f32 v205, v158, v157
	v_mul_f32_e32 v157, 0xbfb8aa3b, v67
	v_mul_f32_e32 v132, 0xbfb8aa3b, v64
	v_mul_f32_e32 v153, 0xbfb8aa3b, v65
	v_mul_f32_e32 v156, 0xbfb8aa3b, v66
	v_exp_f32_e32 v157, v157
	v_exp_f32_e32 v132, v132
	v_exp_f32_e32 v153, v153
	v_exp_f32_e32 v156, v156
	v_add_f32_e32 v157, 1.0, v157
	v_add_f32_e32 v132, 1.0, v132
	v_add_f32_e32 v153, 1.0, v153
	v_add_f32_e32 v156, 1.0, v156
	v_rcp_f32_e32 v157, v157
	v_rcp_f32_e32 v132, v132
	v_rcp_f32_e32 v153, v153
	v_rcp_f32_e32 v156, v156
	v_mul_f32_e32 v157, v67, v157
	v_mul_f32_e32 v132, v64, v132
	v_mul_f32_e32 v153, v65, v153
	v_mul_f32_e32 v158, v66, v156
	v_cvt_pk_bf16_f32 v206, v132, v153
	v_cvt_pk_bf16_f32 v207, v158, v157
	s_nop 1
	v_permlane16_swap_b32_e32 v204, v206
	v_permlane16_swap_b32_e32 v205, v207
	global_store_dwordx4 v[154:155], v[204:207], off offset:256
	v_mul_f32_e32 v157, 0xbfb8aa3b, v63
	v_mul_f32_e32 v132, 0xbfb8aa3b, v60
	v_mul_f32_e32 v153, 0xbfb8aa3b, v61
	v_mul_f32_e32 v156, 0xbfb8aa3b, v62
	v_exp_f32_e32 v157, v157
	v_exp_f32_e32 v132, v132
	v_exp_f32_e32 v153, v153
	v_exp_f32_e32 v156, v156
	v_add_u32_e32 v154, 0x80, v152
	v_add_f32_e32 v157, 1.0, v157
	v_ashrrev_i32_e32 v155, 31, v154
	v_add_f32_e32 v132, 1.0, v132
	v_add_f32_e32 v153, 1.0, v153
	v_add_f32_e32 v156, 1.0, v156
	v_rcp_f32_e32 v157, v157
	v_lshlrev_b64 v[154:155], 12, v[154:155]
	v_rcp_f32_e32 v132, v132
	v_rcp_f32_e32 v153, v153
	v_rcp_f32_e32 v156, v156
	v_lshl_add_u64 v[154:155], s[8:9], 0, v[154:155]
	v_lshl_add_u64 v[154:155], v[154:155], 0, s[0:1]
	v_mul_f32_e32 v157, v63, v157
	v_lshl_add_u64 v[154:155], v[154:155], 0, s[18:19]
	v_mul_f32_e32 v132, v60, v132
	v_mul_f32_e32 v153, v61, v153
	v_mul_f32_e32 v158, v62, v156
	v_cvt_pk_bf16_f32 v200, v132, v153
	v_cvt_pk_bf16_f32 v201, v158, v157
	v_lshl_add_u64 v[154:155], v[154:155], 0, v[208:209]
	v_mul_f32_e32 v157, 0xbfb8aa3b, v55
	v_mul_f32_e32 v132, 0xbfb8aa3b, v52
	v_mul_f32_e32 v153, 0xbfb8aa3b, v53
	v_mul_f32_e32 v156, 0xbfb8aa3b, v54
	v_exp_f32_e32 v157, v157
	v_exp_f32_e32 v132, v132
	v_exp_f32_e32 v153, v153
	v_exp_f32_e32 v156, v156
	v_add_f32_e32 v157, 1.0, v157
	v_add_f32_e32 v132, 1.0, v132
	v_add_f32_e32 v153, 1.0, v153
	v_add_f32_e32 v156, 1.0, v156
	v_rcp_f32_e32 v157, v157
	v_rcp_f32_e32 v132, v132
	v_rcp_f32_e32 v153, v153
	v_rcp_f32_e32 v156, v156
	v_mul_f32_e32 v157, v55, v157
	v_mul_f32_e32 v132, v52, v132
	v_mul_f32_e32 v153, v53, v153
	v_mul_f32_e32 v158, v54, v156
	v_cvt_pk_bf16_f32 v202, v132, v153
	v_cvt_pk_bf16_f32 v203, v158, v157
	s_nop 1
	v_permlane16_swap_b32_e32 v200, v202
	v_permlane16_swap_b32_e32 v201, v203
	global_store_dwordx4 v[154:155], v[200:203], off
	v_mul_f32_e32 v157, 0xbfb8aa3b, v59
	v_mul_f32_e32 v132, 0xbfb8aa3b, v56
	v_mul_f32_e32 v153, 0xbfb8aa3b, v57
	v_mul_f32_e32 v156, 0xbfb8aa3b, v58
	v_exp_f32_e32 v157, v157
	v_exp_f32_e32 v132, v132
	v_exp_f32_e32 v153, v153
	v_exp_f32_e32 v156, v156
	v_add_f32_e32 v157, 1.0, v157
	v_add_f32_e32 v132, 1.0, v132
	v_add_f32_e32 v153, 1.0, v153
	v_add_f32_e32 v156, 1.0, v156
	v_rcp_f32_e32 v157, v157
	v_rcp_f32_e32 v132, v132
	v_rcp_f32_e32 v153, v153
	v_rcp_f32_e32 v156, v156
	v_mul_f32_e32 v157, v59, v157
	v_mul_f32_e32 v132, v56, v132
	v_mul_f32_e32 v153, v57, v153
	v_mul_f32_e32 v158, v58, v156
	v_cvt_pk_bf16_f32 v204, v132, v153
	v_cvt_pk_bf16_f32 v205, v158, v157
	v_mul_f32_e32 v157, 0xbfb8aa3b, v51
	v_mul_f32_e32 v132, 0xbfb8aa3b, v48
	v_mul_f32_e32 v153, 0xbfb8aa3b, v49
	v_mul_f32_e32 v156, 0xbfb8aa3b, v50
	v_exp_f32_e32 v157, v157
	v_exp_f32_e32 v132, v132
	v_exp_f32_e32 v153, v153
	v_exp_f32_e32 v156, v156
	v_add_f32_e32 v157, 1.0, v157
	v_add_f32_e32 v132, 1.0, v132
	v_add_f32_e32 v153, 1.0, v153
	v_add_f32_e32 v156, 1.0, v156
	v_rcp_f32_e32 v157, v157
	v_rcp_f32_e32 v132, v132
	v_rcp_f32_e32 v153, v153
	v_rcp_f32_e32 v156, v156
	v_mul_f32_e32 v157, v51, v157
	v_mul_f32_e32 v132, v48, v132
	v_mul_f32_e32 v153, v49, v153
	v_mul_f32_e32 v158, v50, v156
	v_cvt_pk_bf16_f32 v206, v132, v153
	v_cvt_pk_bf16_f32 v207, v158, v157
	s_nop 1
	v_permlane16_swap_b32_e32 v204, v206
	v_permlane16_swap_b32_e32 v205, v207
	global_store_dwordx4 v[154:155], v[204:207], off offset:256
	v_mul_f32_e32 v157, 0xbfb8aa3b, v47
	v_mul_f32_e32 v132, 0xbfb8aa3b, v44
	v_mul_f32_e32 v153, 0xbfb8aa3b, v45
	v_mul_f32_e32 v156, 0xbfb8aa3b, v46
	v_exp_f32_e32 v157, v157
	v_exp_f32_e32 v132, v132
	v_exp_f32_e32 v153, v153
	v_exp_f32_e32 v156, v156
	v_add_u32_e32 v154, 0x90, v152
	v_add_f32_e32 v157, 1.0, v157
	v_ashrrev_i32_e32 v155, 31, v154
	v_add_f32_e32 v132, 1.0, v132
	v_add_f32_e32 v153, 1.0, v153
	v_add_f32_e32 v156, 1.0, v156
	v_rcp_f32_e32 v157, v157
	v_lshlrev_b64 v[154:155], 12, v[154:155]
	v_rcp_f32_e32 v132, v132
	v_rcp_f32_e32 v153, v153
	v_rcp_f32_e32 v156, v156
	v_lshl_add_u64 v[154:155], s[8:9], 0, v[154:155]
	v_lshl_add_u64 v[154:155], v[154:155], 0, s[0:1]
	v_mul_f32_e32 v157, v47, v157
	v_lshl_add_u64 v[154:155], v[154:155], 0, s[18:19]
	v_mul_f32_e32 v132, v44, v132
	v_mul_f32_e32 v153, v45, v153
	v_mul_f32_e32 v158, v46, v156
	v_cvt_pk_bf16_f32 v200, v132, v153
	v_cvt_pk_bf16_f32 v201, v158, v157
	v_lshl_add_u64 v[154:155], v[154:155], 0, v[208:209]
	v_mul_f32_e32 v157, 0xbfb8aa3b, v39
	v_mul_f32_e32 v132, 0xbfb8aa3b, v36
	v_mul_f32_e32 v153, 0xbfb8aa3b, v37
	v_mul_f32_e32 v156, 0xbfb8aa3b, v38
	v_exp_f32_e32 v157, v157
	v_exp_f32_e32 v132, v132
	v_exp_f32_e32 v153, v153
	v_exp_f32_e32 v156, v156
	v_add_f32_e32 v157, 1.0, v157
	v_add_f32_e32 v132, 1.0, v132
	v_add_f32_e32 v153, 1.0, v153
	v_add_f32_e32 v156, 1.0, v156
	v_rcp_f32_e32 v157, v157
	v_rcp_f32_e32 v132, v132
	v_rcp_f32_e32 v153, v153
	v_rcp_f32_e32 v156, v156
	v_mul_f32_e32 v157, v39, v157
	v_mul_f32_e32 v132, v36, v132
	v_mul_f32_e32 v153, v37, v153
	v_mul_f32_e32 v158, v38, v156
	v_cvt_pk_bf16_f32 v202, v132, v153
	v_cvt_pk_bf16_f32 v203, v158, v157
	s_nop 1
	v_permlane16_swap_b32_e32 v200, v202
	v_permlane16_swap_b32_e32 v201, v203
	global_store_dwordx4 v[154:155], v[200:203], off
	v_mul_f32_e32 v157, 0xbfb8aa3b, v43
	v_mul_f32_e32 v132, 0xbfb8aa3b, v40
	v_mul_f32_e32 v153, 0xbfb8aa3b, v41
	v_mul_f32_e32 v156, 0xbfb8aa3b, v42
	v_exp_f32_e32 v157, v157
	v_exp_f32_e32 v132, v132
	v_exp_f32_e32 v153, v153
	v_exp_f32_e32 v156, v156
	v_add_f32_e32 v157, 1.0, v157
	v_add_f32_e32 v132, 1.0, v132
	v_add_f32_e32 v153, 1.0, v153
	v_add_f32_e32 v156, 1.0, v156
	v_rcp_f32_e32 v157, v157
	v_rcp_f32_e32 v132, v132
	v_rcp_f32_e32 v153, v153
	v_rcp_f32_e32 v156, v156
	v_mul_f32_e32 v157, v43, v157
	v_mul_f32_e32 v132, v40, v132
	v_mul_f32_e32 v153, v41, v153
	v_mul_f32_e32 v158, v42, v156
	v_cvt_pk_bf16_f32 v204, v132, v153
	v_cvt_pk_bf16_f32 v205, v158, v157
	v_mul_f32_e32 v157, 0xbfb8aa3b, v35
	v_mul_f32_e32 v132, 0xbfb8aa3b, v32
	v_mul_f32_e32 v153, 0xbfb8aa3b, v33
	v_mul_f32_e32 v156, 0xbfb8aa3b, v34
	v_exp_f32_e32 v157, v157
	v_exp_f32_e32 v132, v132
	v_exp_f32_e32 v153, v153
	v_exp_f32_e32 v156, v156
	v_add_f32_e32 v157, 1.0, v157
	v_add_f32_e32 v132, 1.0, v132
	v_add_f32_e32 v153, 1.0, v153
	v_add_f32_e32 v156, 1.0, v156
	v_rcp_f32_e32 v157, v157
	v_rcp_f32_e32 v132, v132
	v_rcp_f32_e32 v153, v153
	v_rcp_f32_e32 v156, v156
	v_mul_f32_e32 v157, v35, v157
	v_mul_f32_e32 v132, v32, v132
	v_mul_f32_e32 v153, v33, v153
	v_mul_f32_e32 v158, v34, v156
	v_cvt_pk_bf16_f32 v206, v132, v153
	v_cvt_pk_bf16_f32 v207, v158, v157
	s_nop 1
	v_permlane16_swap_b32_e32 v204, v206
	v_permlane16_swap_b32_e32 v205, v207
	global_store_dwordx4 v[154:155], v[204:207], off offset:256
	v_mul_f32_e32 v157, 0xbfb8aa3b, v31
	v_mul_f32_e32 v132, 0xbfb8aa3b, v28
	v_mul_f32_e32 v153, 0xbfb8aa3b, v29
	v_mul_f32_e32 v156, 0xbfb8aa3b, v30
	v_exp_f32_e32 v157, v157
	v_exp_f32_e32 v132, v132
	v_exp_f32_e32 v153, v153
	v_exp_f32_e32 v156, v156
	v_add_u32_e32 v154, 0xa0, v152
	v_add_f32_e32 v157, 1.0, v157
	v_ashrrev_i32_e32 v155, 31, v154
	v_add_f32_e32 v132, 1.0, v132
	v_add_f32_e32 v153, 1.0, v153
	v_add_f32_e32 v156, 1.0, v156
	v_rcp_f32_e32 v157, v157
	v_lshlrev_b64 v[154:155], 12, v[154:155]
	v_rcp_f32_e32 v132, v132
	v_rcp_f32_e32 v153, v153
	v_rcp_f32_e32 v156, v156
	v_lshl_add_u64 v[154:155], s[8:9], 0, v[154:155]
	v_lshl_add_u64 v[154:155], v[154:155], 0, s[0:1]
	v_mul_f32_e32 v157, v31, v157
	v_lshl_add_u64 v[154:155], v[154:155], 0, s[18:19]
	v_mul_f32_e32 v132, v28, v132
	v_mul_f32_e32 v153, v29, v153
	v_mul_f32_e32 v158, v30, v156
	v_cvt_pk_bf16_f32 v200, v132, v153
	v_cvt_pk_bf16_f32 v201, v158, v157
	v_lshl_add_u64 v[154:155], v[154:155], 0, v[208:209]
	v_mul_f32_e32 v157, 0xbfb8aa3b, v23
	v_mul_f32_e32 v132, 0xbfb8aa3b, v20
	v_mul_f32_e32 v153, 0xbfb8aa3b, v21
	v_mul_f32_e32 v156, 0xbfb8aa3b, v22
	v_exp_f32_e32 v157, v157
	v_exp_f32_e32 v132, v132
	v_exp_f32_e32 v153, v153
	v_exp_f32_e32 v156, v156
	v_add_f32_e32 v157, 1.0, v157
	v_add_f32_e32 v132, 1.0, v132
	v_add_f32_e32 v153, 1.0, v153
	v_add_f32_e32 v156, 1.0, v156
	v_rcp_f32_e32 v157, v157
	v_rcp_f32_e32 v132, v132
	v_rcp_f32_e32 v153, v153
	v_rcp_f32_e32 v156, v156
	v_mul_f32_e32 v157, v23, v157
	v_mul_f32_e32 v132, v20, v132
	v_mul_f32_e32 v153, v21, v153
	v_mul_f32_e32 v158, v22, v156
	v_cvt_pk_bf16_f32 v202, v132, v153
	v_cvt_pk_bf16_f32 v203, v158, v157
	s_nop 1
	v_permlane16_swap_b32_e32 v200, v202
	v_permlane16_swap_b32_e32 v201, v203
	global_store_dwordx4 v[154:155], v[200:203], off
	v_mul_f32_e32 v157, 0xbfb8aa3b, v27
	v_mul_f32_e32 v132, 0xbfb8aa3b, v24
	v_mul_f32_e32 v153, 0xbfb8aa3b, v25
	v_mul_f32_e32 v156, 0xbfb8aa3b, v26
	v_exp_f32_e32 v157, v157
	v_exp_f32_e32 v132, v132
	v_exp_f32_e32 v153, v153
	v_exp_f32_e32 v156, v156
	v_add_f32_e32 v157, 1.0, v157
	v_add_f32_e32 v132, 1.0, v132
	v_add_f32_e32 v153, 1.0, v153
	v_add_f32_e32 v156, 1.0, v156
	v_rcp_f32_e32 v157, v157
	v_rcp_f32_e32 v132, v132
	v_rcp_f32_e32 v153, v153
	v_rcp_f32_e32 v156, v156
	v_mul_f32_e32 v157, v27, v157
	v_mul_f32_e32 v132, v24, v132
	v_mul_f32_e32 v153, v25, v153
	v_mul_f32_e32 v158, v26, v156
	v_cvt_pk_bf16_f32 v204, v132, v153
	v_cvt_pk_bf16_f32 v205, v158, v157
	v_mul_f32_e32 v157, 0xbfb8aa3b, v19
	v_mul_f32_e32 v132, 0xbfb8aa3b, v16
	v_mul_f32_e32 v153, 0xbfb8aa3b, v17
	v_mul_f32_e32 v156, 0xbfb8aa3b, v18
	v_exp_f32_e32 v157, v157
	v_exp_f32_e32 v132, v132
	v_exp_f32_e32 v153, v153
	v_exp_f32_e32 v156, v156
	v_add_f32_e32 v157, 1.0, v157
	v_add_f32_e32 v132, 1.0, v132
	v_add_f32_e32 v153, 1.0, v153
	v_add_f32_e32 v156, 1.0, v156
	v_rcp_f32_e32 v157, v157
	v_rcp_f32_e32 v132, v132
	v_rcp_f32_e32 v153, v153
	v_rcp_f32_e32 v156, v156
	v_mul_f32_e32 v157, v19, v157
	v_mul_f32_e32 v132, v16, v132
	v_mul_f32_e32 v153, v17, v153
	v_mul_f32_e32 v158, v18, v156
	v_cvt_pk_bf16_f32 v206, v132, v153
	v_cvt_pk_bf16_f32 v207, v158, v157
	s_nop 1
	v_permlane16_swap_b32_e32 v204, v206
	v_permlane16_swap_b32_e32 v205, v207
	global_store_dwordx4 v[154:155], v[204:207], off offset:256
	v_mul_f32_e32 v154, 0xbfb8aa3b, v13
	v_mul_f32_e32 v155, 0xbfb8aa3b, v14
	v_mul_f32_e32 v132, 0xbfb8aa3b, v12
	v_exp_f32_e32 v154, v154
	v_exp_f32_e32 v155, v155
	v_mul_f32_e32 v156, 0xbfb8aa3b, v15
	v_exp_f32_e32 v132, v132
	v_exp_f32_e32 v156, v156
	v_add_u32_e32 v152, 0xb0, v152
	v_add_f32_e32 v154, 1.0, v154
	v_add_f32_e32 v155, 1.0, v155
	v_ashrrev_i32_e32 v153, 31, v152
	v_add_f32_e32 v132, 1.0, v132
	v_rcp_f32_e32 v154, v154
	v_rcp_f32_e32 v155, v155
	v_add_f32_e32 v156, 1.0, v156
	v_lshlrev_b64 v[152:153], 12, v[152:153]
	v_rcp_f32_e32 v132, v132
	v_rcp_f32_e32 v156, v156
	v_lshl_add_u64 v[152:153], s[8:9], 0, v[152:153]
	v_lshl_add_u64 v[152:153], v[152:153], 0, s[0:1]
	v_mul_f32_e32 v154, v13, v154
	v_mul_f32_e32 v155, v14, v155
	v_lshl_add_u64 v[152:153], v[152:153], 0, s[18:19]
	v_mul_f32_e32 v132, v12, v132
	v_mul_f32_e32 v156, v15, v156
	v_cvt_pk_bf16_f32 v200, v132, v154
	v_cvt_pk_bf16_f32 v201, v155, v156
	v_lshl_add_u64 v[152:153], v[152:153], 0, v[208:209]
	v_mul_f32_e32 v155, 0xbfb8aa3b, v7
	v_mul_f32_e32 v132, 0xbfb8aa3b, v4
	v_mul_f32_e32 v151, 0xbfb8aa3b, v5
	v_mul_f32_e32 v154, 0xbfb8aa3b, v6
	v_exp_f32_e32 v155, v155
	v_exp_f32_e32 v132, v132
	v_exp_f32_e32 v151, v151
	v_exp_f32_e32 v154, v154
	v_add_f32_e32 v155, 1.0, v155
	v_add_f32_e32 v132, 1.0, v132
	v_add_f32_e32 v151, 1.0, v151
	v_add_f32_e32 v154, 1.0, v154
	v_rcp_f32_e32 v155, v155
	v_rcp_f32_e32 v132, v132
	v_rcp_f32_e32 v151, v151
	v_rcp_f32_e32 v154, v154
	v_mul_f32_e32 v155, v7, v155
	v_mul_f32_e32 v132, v4, v132
	v_mul_f32_e32 v151, v5, v151
	v_mul_f32_e32 v156, v6, v154
	v_cvt_pk_bf16_f32 v202, v132, v151
	v_cvt_pk_bf16_f32 v203, v156, v155
	s_nop 1
	v_permlane16_swap_b32_e32 v200, v202
	v_permlane16_swap_b32_e32 v201, v203
	global_store_dwordx4 v[152:153], v[200:203], off
	v_mul_f32_e32 v155, 0xbfb8aa3b, v11
	v_mul_f32_e32 v132, 0xbfb8aa3b, v8
	v_mul_f32_e32 v151, 0xbfb8aa3b, v9
	v_mul_f32_e32 v154, 0xbfb8aa3b, v10
	v_exp_f32_e32 v155, v155
	v_exp_f32_e32 v132, v132
	v_exp_f32_e32 v151, v151
	v_exp_f32_e32 v154, v154
	v_add_f32_e32 v155, 1.0, v155
	v_add_f32_e32 v132, 1.0, v132
	v_add_f32_e32 v151, 1.0, v151
	v_add_f32_e32 v154, 1.0, v154
	v_rcp_f32_e32 v155, v155
	v_rcp_f32_e32 v132, v132
	v_rcp_f32_e32 v151, v151
	v_rcp_f32_e32 v154, v154
	v_mul_f32_e32 v155, v11, v155
	v_mul_f32_e32 v132, v8, v132
	v_mul_f32_e32 v151, v9, v151
	v_mul_f32_e32 v156, v10, v154
	v_cvt_pk_bf16_f32 v204, v132, v151
	v_cvt_pk_bf16_f32 v205, v156, v155
	v_mul_f32_e32 v155, 0xbfb8aa3b, v3
	v_mul_f32_e32 v132, 0xbfb8aa3b, v0
	v_mul_f32_e32 v151, 0xbfb8aa3b, v1
	v_mul_f32_e32 v154, 0xbfb8aa3b, v2
	v_exp_f32_e32 v155, v155
	v_exp_f32_e32 v132, v132
	v_exp_f32_e32 v151, v151
	v_exp_f32_e32 v154, v154
	v_add_f32_e32 v155, 1.0, v155
	v_add_f32_e32 v132, 1.0, v132
	v_add_f32_e32 v151, 1.0, v151
	v_add_f32_e32 v154, 1.0, v154
	v_rcp_f32_e32 v155, v155
	v_rcp_f32_e32 v132, v132
	v_rcp_f32_e32 v151, v151
	v_rcp_f32_e32 v154, v154
	v_mul_f32_e32 v155, v3, v155
	s_mov_b64 s[0:1], 0
	v_mul_f32_e32 v132, v0, v132
	v_mul_f32_e32 v151, v1, v151
	v_mul_f32_e32 v156, v2, v154
	v_cvt_pk_bf16_f32 v206, v132, v151
	v_cvt_pk_bf16_f32 v207, v156, v155
	s_nop 1
	v_permlane16_swap_b32_e32 v204, v206
	v_permlane16_swap_b32_e32 v205, v207
	global_store_dwordx4 v[152:153], v[204:207], off offset:256
